# embedding-LN row loop: gamma/beta/forget-bias hoisted out of the loop, per-row vmcnt(0) drains removed, loop-top waits re-counted
# speedup vs baseline: 1.0232x; 1.0068x over previous
.LBB0_59:
	s_or_b64 exec, exec, s[6:7]
	v_and_b32_e32 v183, 63, v2
	v_ashrrev_i32_e32 v2, 1, v2
	v_and_b32_e32 v149, 0xffffffe0, v2
	v_lshl_add_u32 v2, s39, 8, v149
	v_ashrrev_i32_e32 v3, 31, v2
	v_lshlrev_b64 v[2:3], 12, v[2:3]
	v_lshl_add_u64 v[2:3], s[68:69], 0, v[2:3]
	v_lshlrev_b32_e32 v4, 4, v183
	v_mov_b32_e32 v5, v147
	v_lshl_add_u64 v[2:3], v[2:3], 0, v[4:5]
	s_waitcnt lgkmcnt(0)
	s_barrier
	global_load_dwordx4 v[142:145], v[2:3], off
	global_load_dwordx4 v[138:141], v[2:3], off offset:1024
	global_load_dwordx4 v[134:137], v[2:3], off offset:2048
	global_load_dwordx4 v[130:133], v[2:3], off offset:3072
	v_cmp_lt_i32_e32 vcc, v177, v178
	v_or_b32_e32 v6, 0x19000, v4
	v_or_b32_e32 v10, 0x1a000, v4
	v_cndmask_b32_e32 v2, v175, v177, vcc
	v_cmp_lt_i32_e32 vcc, v179, v178
	v_lshlrev_b32_e32 v184, 2, v2
	v_or_b32_e32 v14, 0x1b000, v4
	v_cndmask_b32_e32 v2, v175, v179, vcc
	v_lshlrev_b32_e32 v185, 2, v2
	v_or_b32_e32 v2, 0x18000, v4
	v_or_b32_e32 v18, 0x1c000, v4
	v_or_b32_e32 v22, 0x1d000, v4
	v_or_b32_e32 v26, 0x1e000, v4
	v_or_b32_e32 v30, 0x1f000, v4
	v_or_b32_e32 v34, 0x18400, v4
	v_or_b32_e32 v38, 0x19400, v4
	v_or_b32_e32 v42, 0x1a400, v4
	v_or_b32_e32 v46, 0x1b400, v4
	v_or_b32_e32 v50, 0x1c400, v4
	v_or_b32_e32 v54, 0x1d400, v4
	v_or_b32_e32 v58, 0x1e400, v4
	v_or_b32_e32 v62, 0x1f400, v4
	v_or_b32_e32 v66, 0x18800, v4
	v_or_b32_e32 v70, 0x19800, v4
	v_or_b32_e32 v74, 0x1a800, v4
	v_or_b32_e32 v78, 0x1b800, v4
	v_or_b32_e32 v82, 0x1c800, v4
	v_or_b32_e32 v86, 0x1d800, v4
	v_or_b32_e32 v90, 0x1e800, v4
	v_or_b32_e32 v94, 0x1f800, v4
	v_or_b32_e32 v98, 0x18c00, v4
	v_or_b32_e32 v102, 0x19c00, v4
	v_or_b32_e32 v106, 0x1ac00, v4
	v_or_b32_e32 v110, 0x1bc00, v4
	v_or_b32_e32 v114, 0x1cc00, v4
	v_or_b32_e32 v118, 0x1dc00, v4
	v_or_b32_e32 v122, 0x1ec00, v4
	v_or_b32_e32 v126, 0x1fc00, v4
	v_lshl_add_u64 v[150:151], s[68:69], 0, v[4:5]
	v_lshl_add_u64 v[152:153], s[72:73], 0, v[4:5]
	v_lshl_add_u64 v[154:155], s[74:75], 0, v[4:5]
	ds_read_b128 v[2:5], v2
	ds_read_b128 v[6:9], v6
	ds_read_b128 v[10:13], v10
	ds_read_b128 v[14:17], v14
	ds_read_b128 v[18:21], v18
	ds_read_b128 v[22:25], v22
	ds_read_b128 v[26:29], v26
	ds_read_b128 v[30:33], v30
	ds_read_b128 v[34:37], v34
	ds_read_b128 v[38:41], v38
	ds_read_b128 v[42:45], v42
	ds_read_b128 v[46:49], v46
	ds_read_b128 v[50:53], v50
	ds_read_b128 v[54:57], v54
	ds_read_b128 v[58:61], v58
	ds_read_b128 v[62:65], v62
	ds_read_b128 v[66:69], v66
	ds_read_b128 v[70:73], v70
	ds_read_b128 v[74:77], v74
	ds_read_b128 v[78:81], v78
	ds_read_b128 v[82:85], v82
	ds_read_b128 v[86:89], v86
	ds_read_b128 v[90:93], v90
	ds_read_b128 v[94:97], v94
	ds_read_b128 v[98:101], v98
	ds_read_b128 v[102:105], v102
	ds_read_b128 v[106:109], v106
	ds_read_b128 v[110:113], v110
	ds_read_b128 v[114:117], v114
	ds_read_b128 v[118:121], v118
	ds_read_b128 v[122:125], v122
	ds_read_b128 v[126:129], v126
	s_add_u32 s18, s96, s4
	v_lshlrev_b32_e32 v146, 2, v183
	s_addc_u32 s19, s97, s5
	v_lshl_add_u64 v[156:157], s[78:79], 0, v[146:147]
	v_lshlrev_b32_e32 v146, 3, v183
	s_add_u32 s22, s18, 0x1a00000
	v_lshl_add_u64 v[158:159], s[18:19], 0, v[146:147]
	s_addc_u32 s23, s19, 0
	s_mov_b32 s40, 0
	v_cmp_gt_u32_e32 vcc, 8, v183
	v_cmp_eq_u32_e64 s[0:1], 7, v183
	v_cmp_eq_u32_e64 s[16:17], 6, v183
	v_cmp_eq_u32_e64 s[4:5], 5, v183
	v_cmp_eq_u32_e64 s[6:7], 4, v183
	v_cmp_eq_u32_e64 s[8:9], 3, v183
	v_cmp_eq_u32_e64 s[10:11], 2, v183
	v_cmp_eq_u32_e64 s[12:13], 1, v183
	v_cmp_eq_u32_e64 s[14:15], 0, v183
	v_lshl_add_u64 v[158:159], v[158:159], 0, s[20:21]
	v_add_u32_e32 v186, s3, v149
	global_load_dwordx4 v[214:217], v[152:153], off
	global_load_dwordx4 v[218:221], v[152:153], off offset:1024
	global_load_dwordx4 v[222:225], v[152:153], off offset:2048
	global_load_dwordx4 v[226:229], v[152:153], off offset:3072
	global_load_dwordx4 v[230:233], v[154:155], off
	global_load_dwordx4 v[234:237], v[154:155], off offset:1024
	global_load_dwordx4 v[238:241], v[154:155], off offset:2048
	global_load_dwordx4 v[242:245], v[154:155], off offset:3072
	global_load_dword v246, v[156:157], off
	s_waitcnt vmcnt(0)
	s_branch .LBB0_61

.LBB0_61:
	s_waitcnt lgkmcnt(0)
	s_waitcnt vmcnt(8)
	v_mov_b32_e32 v160, v142
	s_waitcnt vmcnt(7)
	v_mov_b32_e32 v161, v138
	v_mov_b32_e32 v162, v143
	v_mov_b32_e32 v163, v139
	v_pk_add_f32 v[160:161], v[160:161], v[162:163]
	v_mov_b32_e32 v162, v144
	v_mov_b32_e32 v163, v140
	v_pk_add_f32 v[160:161], v[160:161], v[162:163]
	v_mov_b32_e32 v162, v145
	v_mov_b32_e32 v163, v141
	v_pk_add_f32 v[160:161], v[160:161], v[162:163]
	s_waitcnt vmcnt(6)
	v_mov_b32_e32 v162, v135
	v_add_f32_e32 v146, 0, v160
	v_add_f32_e32 v146, v146, v161
	v_mov_b32_e32 v160, v134
	s_waitcnt vmcnt(5)
	v_mov_b32_e32 v161, v130
	v_mov_b32_e32 v163, v131
	v_pk_add_f32 v[160:161], v[160:161], v[162:163]
	v_mov_b32_e32 v162, v136
	v_mov_b32_e32 v163, v132
	v_pk_add_f32 v[160:161], v[160:161], v[162:163]
	v_mov_b32_e32 v162, v137
	v_mov_b32_e32 v163, v133
	v_pk_add_f32 v[160:161], v[160:161], v[162:163]
	s_cmp_lg_u32 s40, 31
	v_add_f32_e32 v146, v146, v160
	v_add_f32_e32 v146, v146, v161
	v_mov_b32_e32 v161, s40
	s_cselect_b64 s[18:19], -1, 0
	v_add_f32_dpp v146, v146, v146 quad_perm:[1,0,3,2] row_mask:0xf bank_mask:0xf bound_ctrl:1
	v_add_u32_e32 v160, s40, v186
	s_nop 0
	v_add_f32_dpp v146, v146, v146 quad_perm:[2,3,0,1] row_mask:0xf bank_mask:0xf bound_ctrl:1
	s_nop 1
	v_add_f32_dpp v146, v146, v146 row_ror:4 row_mask:0xf bank_mask:0xf bound_ctrl:1
	s_nop 1
	v_add_f32_dpp v146, v146, v146 row_ror:8 row_mask:0xf bank_mask:0xf bound_ctrl:1
	ds_bpermute_b32 v149, v184, v146
	s_waitcnt lgkmcnt(0)
	v_add_f32_e32 v146, v146, v149
	ds_bpermute_b32 v149, v185, v146
	s_waitcnt lgkmcnt(0)
	v_add_f32_e32 v146, v146, v149
	v_mul_f32_e32 v146, 0x3a800000, v146
	v_pk_add_f32 v[170:171], v[142:143], v[146:147] op_sel_hi:[1,0] neg_lo:[0,1] neg_hi:[0,1]
	v_pk_add_f32 v[168:169], v[144:145], v[146:147] op_sel_hi:[1,0] neg_lo:[0,1] neg_hi:[0,1]
	v_pk_mul_f32 v[142:143], v[170:171], v[170:171]
	v_pk_mul_f32 v[144:145], v[168:169], v[168:169]
	v_add_f32_e32 v142, v142, v143
	v_pk_add_f32 v[198:199], v[138:139], v[146:147] op_sel_hi:[1,0] neg_lo:[0,1] neg_hi:[0,1]
	v_add_f32_e32 v142, v144, v142
	v_pk_mul_f32 v[138:139], v[198:199], v[198:199]
	v_add_f32_e32 v142, v145, v142
	v_pk_add_f32 v[196:197], v[140:141], v[146:147] op_sel_hi:[1,0] neg_lo:[0,1] neg_hi:[0,1]
	v_add_f32_e32 v138, v138, v142
	v_pk_mul_f32 v[140:141], v[196:197], v[196:197]
	v_add_f32_e32 v138, v139, v138
	v_pk_add_f32 v[202:203], v[134:135], v[146:147] op_sel_hi:[1,0] neg_lo:[0,1] neg_hi:[0,1]
	v_add_f32_e32 v138, v140, v138
	v_pk_mul_f32 v[134:135], v[202:203], v[202:203]
	v_add_f32_e32 v138, v141, v138
	v_pk_add_f32 v[200:201], v[136:137], v[146:147] op_sel_hi:[1,0] neg_lo:[0,1] neg_hi:[0,1]
	v_add_f32_e32 v134, v134, v138
	v_pk_mul_f32 v[136:137], v[200:201], v[200:201]
	v_add_f32_e32 v134, v135, v134
	v_pk_add_f32 v[166:167], v[130:131], v[146:147] op_sel_hi:[1,0] neg_lo:[0,1] neg_hi:[0,1]
	v_add_f32_e32 v134, v136, v134
	v_pk_mul_f32 v[130:131], v[166:167], v[166:167]
	v_add_f32_e32 v134, v137, v134
	v_pk_add_f32 v[164:165], v[132:133], v[146:147] op_sel_hi:[1,0] neg_lo:[0,1] neg_hi:[0,1]
	v_add_f32_e32 v130, v130, v134
	v_pk_mul_f32 v[132:133], v[164:165], v[164:165]
	v_add_f32_e32 v130, v131, v130
	v_add_f32_e32 v130, v132, v130
	v_add_f32_e32 v130, v133, v130
	s_nop 1
	v_add_f32_dpp v130, v130, v130 quad_perm:[1,0,3,2] row_mask:0xf bank_mask:0xf bound_ctrl:1
	s_nop 1
	v_add_f32_dpp v130, v130, v130 quad_perm:[2,3,0,1] row_mask:0xf bank_mask:0xf bound_ctrl:1
	s_nop 1
	v_add_f32_dpp v130, v130, v130 row_ror:4 row_mask:0xf bank_mask:0xf bound_ctrl:1
	s_nop 1
	v_add_f32_dpp v132, v130, v130 row_ror:8 row_mask:0xf bank_mask:0xf bound_ctrl:1
	ds_bpermute_b32 v133, v184, v132
	v_addc_co_u32_e64 v130, s[18:19], v186, v161, s[18:19]
	v_ashrrev_i32_e32 v131, 31, v130
	v_ashrrev_i32_e32 v161, 31, v160
	s_waitcnt lgkmcnt(0)
	v_add_f32_e32 v146, v132, v133
	ds_bpermute_b32 v149, v185, v146
	v_lshlrev_b64 v[130:131], 12, v[130:131]
	v_lshlrev_b64 v[162:163], 11, v[160:161]
	v_lshl_add_u64 v[130:131], v[150:151], 0, v[130:131]
	v_lshl_add_u64 v[162:163], v[158:159], 0, v[162:163]
	s_waitcnt lgkmcnt(0)
	v_add_f32_e32 v146, v146, v149
	v_fmamk_f32 v146, v146, 0x3a800000, v1
	v_mul_f32_e32 v149, 0x4b800000, v146
	v_cmp_gt_f32_e64 s[18:19], s33, v146
	global_load_dwordx4 v[142:145], v[130:131], off
	global_load_dwordx4 v[138:141], v[130:131], off offset:1024
	global_load_dwordx4 v[134:137], v[130:131], off offset:2048
	s_nop 0
	global_load_dwordx4 v[130:133], v[130:131], off offset:3072
	v_cndmask_b32_e64 v146, v146, v149, s[18:19]
	v_rsq_f32_e32 v146, v146
	s_nop 0
	v_mul_f32_e32 v149, 0x45800000, v146
	v_cndmask_b32_e64 v146, v146, v149, s[18:19]
	v_pk_mul_f32 v[170:171], v[170:171], v[146:147] op_sel_hi:[1,0]
	v_pk_mul_f32 v[168:169], v[168:169], v[146:147] op_sel_hi:[1,0]
	v_pk_fma_f32 v[170:171], v[214:215], v[170:171], v[230:231]
	v_pk_fma_f32 v[168:169], v[216:217], v[168:169], v[232:233]
	v_cvt_pk_bf16_f32 v188, v170, v171
	v_cvt_pk_bf16_f32 v189, v168, v169
	global_store_dwordx2 v[162:163], v[188:189], off
	s_nop 0
	v_pk_mul_f32 v[198:199], v[198:199], v[146:147] op_sel_hi:[1,0]
	v_pk_mul_f32 v[196:197], v[196:197], v[146:147] op_sel_hi:[1,0]
	v_pk_mul_f32 v[206:207], v[164:165], v[146:147] op_sel_hi:[1,0]
	v_mul_f32_e32 v164, v15, v171
	v_mul_f32_e32 v165, v19, v171
	v_fmac_f32_e32 v164, v14, v170
	v_fmac_f32_e32 v165, v18, v170
	v_pk_mul_f32 v[202:203], v[202:203], v[146:147] op_sel_hi:[1,0]
	v_pk_mul_f32 v[200:201], v[200:201], v[146:147] op_sel_hi:[1,0]
	v_pk_mul_f32 v[204:205], v[166:167], v[146:147] op_sel_hi:[1,0]
	v_mul_f32_e32 v146, v3, v171
	v_mul_f32_e32 v149, v7, v171
	v_mul_f32_e32 v161, v11, v171
	v_mul_f32_e32 v166, v171, v23
	v_mul_f32_e32 v167, v171, v27
	v_mul_f32_e32 v171, v171, v31
	v_fmac_f32_e32 v164, v16, v168
	v_fmac_f32_e32 v165, v20, v168
	v_fmac_f32_e32 v166, v170, v22
	v_fmac_f32_e32 v167, v170, v26
	v_fmac_f32_e32 v171, v170, v30
	v_fmac_f32_e32 v164, v17, v169
	v_fmac_f32_e32 v165, v21, v169
	v_fmac_f32_e32 v146, v2, v170
	v_fmac_f32_e32 v149, v6, v170
	v_fmac_f32_e32 v161, v10, v170
	v_fmac_f32_e32 v166, v168, v24
	v_fmac_f32_e32 v167, v168, v28
	v_fmac_f32_e32 v171, v168, v32
	v_add_f32_e32 v187, 0, v164
	v_add_f32_e32 v208, 0, v165
	v_fmac_f32_e32 v146, v4, v168
	v_fmac_f32_e32 v149, v8, v168
	v_fmac_f32_e32 v161, v12, v168
	v_fmac_f32_e32 v166, v169, v25
	v_fmac_f32_e32 v167, v169, v29
	v_fmac_f32_e32 v171, v169, v33
	v_fmac_f32_e32 v146, v5, v169
	v_fmac_f32_e32 v149, v9, v169
	v_fmac_f32_e32 v161, v13, v169
	v_add_f32_e32 v209, 0, v166
	v_add_f32_e32 v210, 0, v167
	v_add_f32_e32 v211, 0, v171
	v_add_f32_e32 v161, 0, v161
	v_add_f32_e32 v149, 0, v149
	v_add_f32_e32 v146, 0, v146
	v_pk_fma_f32 v[198:199], v[198:199], v[218:219], v[234:235]
	v_pk_fma_f32 v[196:197], v[196:197], v[220:221], v[236:237]
	v_cvt_pk_bf16_f32 v188, v198, v199
	v_cvt_pk_bf16_f32 v189, v196, v197
	global_store_dwordx2 v[162:163], v[188:189], off offset:512
	s_nop 0
	v_mul_f32_e32 v212, v199, v35
	v_fmac_f32_e32 v212, v198, v34
	v_fmac_f32_e32 v212, v196, v36
	v_fmac_f32_e32 v212, v197, v37
	v_add_f32_e32 v146, v146, v212
	v_pk_fma_f32 v[188:189], v[202:203], v[222:223], v[238:239]
	v_pk_fma_f32 v[190:191], v[200:201], v[224:225], v[240:241]
	v_cvt_pk_bf16_f32 v164, v188, v189
	v_cvt_pk_bf16_f32 v165, v190, v191
	global_store_dwordx2 v[162:163], v[164:165], off offset:1024
	s_nop 0
	v_mul_f32_e32 v193, v199, v43
	v_mul_f32_e32 v194, v199, v47
	v_mul_f32_e32 v200, v199, v55
	v_mul_f32_e32 v201, v199, v59
	v_mul_f32_e32 v192, v199, v39
	v_mul_f32_e32 v195, v199, v51
	v_mul_f32_e32 v199, v199, v63
	v_fmac_f32_e32 v193, v198, v42
	v_fmac_f32_e32 v194, v198, v46
	v_fmac_f32_e32 v200, v198, v54
	v_fmac_f32_e32 v201, v198, v58
	v_fmac_f32_e32 v192, v198, v38
	v_fmac_f32_e32 v195, v198, v50
	v_fmac_f32_e32 v199, v198, v62
	v_fmac_f32_e32 v193, v196, v44
	v_fmac_f32_e32 v194, v196, v48
	v_fmac_f32_e32 v200, v196, v56
	v_fmac_f32_e32 v201, v196, v60
	v_fmac_f32_e32 v192, v196, v40
	v_fmac_f32_e32 v195, v196, v52
	v_fmac_f32_e32 v199, v196, v64
	v_fmac_f32_e32 v193, v197, v45
	v_fmac_f32_e32 v194, v197, v49
	v_fmac_f32_e32 v200, v197, v57
	v_fmac_f32_e32 v201, v197, v61
	v_fmac_f32_e32 v192, v197, v41
	v_fmac_f32_e32 v195, v197, v53
	v_fmac_f32_e32 v199, v197, v65
	v_add_f32_e32 v161, v161, v193
	v_add_f32_e32 v187, v187, v194
	v_add_f32_e32 v193, v209, v200
	v_add_f32_e32 v194, v210, v201
	v_mul_f32_e32 v200, v189, v83
	v_mul_f32_e32 v201, v189, v87
	v_add_f32_e32 v149, v149, v192
	v_add_f32_e32 v192, v208, v195
	v_add_f32_e32 v195, v211, v199
	v_mul_f32_e32 v196, v189, v67
	v_mul_f32_e32 v197, v189, v71
	v_mul_f32_e32 v198, v189, v75
	v_mul_f32_e32 v199, v189, v79
	v_mul_f32_e32 v202, v189, v91
	v_mul_f32_e32 v189, v189, v95
	v_fmac_f32_e32 v200, v188, v82
	v_fmac_f32_e32 v201, v188, v86
	v_fmac_f32_e32 v202, v188, v90
	v_fmac_f32_e32 v189, v188, v94
	v_fmac_f32_e32 v200, v190, v84
	v_fmac_f32_e32 v201, v190, v88
	v_fmac_f32_e32 v196, v188, v66
	v_fmac_f32_e32 v197, v188, v70
	v_fmac_f32_e32 v198, v188, v74
	v_fmac_f32_e32 v199, v188, v78
	v_fmac_f32_e32 v202, v190, v92
	v_fmac_f32_e32 v189, v190, v96
	v_fmac_f32_e32 v200, v191, v85
	v_fmac_f32_e32 v201, v191, v89
	v_fmac_f32_e32 v196, v190, v68
	v_fmac_f32_e32 v197, v190, v72
	v_fmac_f32_e32 v198, v190, v76
	v_fmac_f32_e32 v199, v190, v80
	v_fmac_f32_e32 v202, v191, v93
	v_fmac_f32_e32 v189, v191, v97
	v_add_f32_e32 v188, v192, v200
	v_add_f32_e32 v190, v193, v201
	v_fmac_f32_e32 v196, v191, v69
	v_fmac_f32_e32 v197, v191, v73
	v_fmac_f32_e32 v198, v191, v77
	v_fmac_f32_e32 v199, v191, v81
	v_add_f32_e32 v191, v194, v202
	v_add_f32_e32 v189, v195, v189
	v_add_f32_e32 v146, v146, v196
	v_add_f32_e32 v149, v149, v197
	v_add_f32_e32 v161, v161, v198
	v_add_f32_e32 v187, v187, v199
	v_pk_fma_f32 v[192:193], v[204:205], v[226:227], v[242:243]
	v_pk_fma_f32 v[194:195], v[206:207], v[228:229], v[244:245]
	v_mul_f32_e32 v164, v193, v99
	v_mul_f32_e32 v165, v193, v103
	v_mul_f32_e32 v166, v193, v107
	v_mul_f32_e32 v167, v193, v111
	v_mul_f32_e32 v168, v193, v115
	v_mul_f32_e32 v169, v193, v119
	v_mul_f32_e32 v170, v193, v123
	v_mul_f32_e32 v171, v193, v127
	v_fmac_f32_e32 v164, v192, v98
	v_fmac_f32_e32 v165, v192, v102
	v_fmac_f32_e32 v166, v192, v106
	v_fmac_f32_e32 v167, v192, v110
	v_fmac_f32_e32 v168, v192, v114
	v_fmac_f32_e32 v169, v192, v118
	v_fmac_f32_e32 v170, v192, v122
	v_fmac_f32_e32 v171, v192, v126
	v_fmac_f32_e32 v164, v194, v100
	v_fmac_f32_e32 v165, v194, v104
	v_fmac_f32_e32 v166, v194, v108
	v_fmac_f32_e32 v167, v194, v112
	v_fmac_f32_e32 v168, v194, v116
	v_fmac_f32_e32 v169, v194, v120
	v_fmac_f32_e32 v170, v194, v124
	v_fmac_f32_e32 v171, v194, v128
	v_fmac_f32_e32 v164, v195, v101
	v_fmac_f32_e32 v165, v195, v105
	v_fmac_f32_e32 v166, v195, v109
	v_fmac_f32_e32 v167, v195, v113
	v_fmac_f32_e32 v168, v195, v117
	v_fmac_f32_e32 v169, v195, v121
	v_fmac_f32_e32 v170, v195, v125
	v_fmac_f32_e32 v171, v195, v129
	v_add_f32_e32 v146, v146, v164
	v_add_f32_e32 v149, v149, v165
	v_add_f32_e32 v161, v161, v166
	v_add_f32_e32 v164, v187, v167
	v_add_f32_e32 v165, v188, v168
	v_add_f32_e32 v166, v190, v169
	v_add_f32_e32 v167, v191, v170
	v_add_f32_e32 v168, v189, v171
	v_add_f32_dpp v146, v146, v146 quad_perm:[1,0,3,2] row_mask:0xf bank_mask:0xf bound_ctrl:1
	v_add_f32_dpp v149, v149, v149 quad_perm:[1,0,3,2] row_mask:0xf bank_mask:0xf bound_ctrl:1
	v_add_f32_dpp v161, v161, v161 quad_perm:[1,0,3,2] row_mask:0xf bank_mask:0xf bound_ctrl:1
	v_add_f32_dpp v164, v164, v164 quad_perm:[1,0,3,2] row_mask:0xf bank_mask:0xf bound_ctrl:1
	v_add_f32_dpp v165, v165, v165 quad_perm:[1,0,3,2] row_mask:0xf bank_mask:0xf bound_ctrl:1
	v_add_f32_dpp v166, v166, v166 quad_perm:[1,0,3,2] row_mask:0xf bank_mask:0xf bound_ctrl:1
	v_add_f32_dpp v167, v167, v167 quad_perm:[1,0,3,2] row_mask:0xf bank_mask:0xf bound_ctrl:1
	v_add_f32_dpp v168, v168, v168 quad_perm:[1,0,3,2] row_mask:0xf bank_mask:0xf bound_ctrl:1
	v_add_f32_dpp v146, v146, v146 quad_perm:[2,3,0,1] row_mask:0xf bank_mask:0xf bound_ctrl:1
	v_add_f32_dpp v149, v149, v149 quad_perm:[2,3,0,1] row_mask:0xf bank_mask:0xf bound_ctrl:1
	v_add_f32_dpp v161, v161, v161 quad_perm:[2,3,0,1] row_mask:0xf bank_mask:0xf bound_ctrl:1
	v_add_f32_dpp v164, v164, v164 quad_perm:[2,3,0,1] row_mask:0xf bank_mask:0xf bound_ctrl:1
	v_add_f32_dpp v165, v165, v165 quad_perm:[2,3,0,1] row_mask:0xf bank_mask:0xf bound_ctrl:1
	v_add_f32_dpp v166, v166, v166 quad_perm:[2,3,0,1] row_mask:0xf bank_mask:0xf bound_ctrl:1
	v_add_f32_dpp v167, v167, v167 quad_perm:[2,3,0,1] row_mask:0xf bank_mask:0xf bound_ctrl:1
	v_add_f32_dpp v168, v168, v168 quad_perm:[2,3,0,1] row_mask:0xf bank_mask:0xf bound_ctrl:1
	v_add_f32_dpp v146, v146, v146 row_ror:4 row_mask:0xf bank_mask:0xf bound_ctrl:1
	v_add_f32_dpp v149, v149, v149 row_ror:4 row_mask:0xf bank_mask:0xf bound_ctrl:1
	v_add_f32_dpp v161, v161, v161 row_ror:4 row_mask:0xf bank_mask:0xf bound_ctrl:1
	v_add_f32_dpp v164, v164, v164 row_ror:4 row_mask:0xf bank_mask:0xf bound_ctrl:1
	v_add_f32_dpp v165, v165, v165 row_ror:4 row_mask:0xf bank_mask:0xf bound_ctrl:1
	v_add_f32_dpp v166, v166, v166 row_ror:4 row_mask:0xf bank_mask:0xf bound_ctrl:1
	v_add_f32_dpp v167, v167, v167 row_ror:4 row_mask:0xf bank_mask:0xf bound_ctrl:1
	v_add_f32_dpp v168, v168, v168 row_ror:4 row_mask:0xf bank_mask:0xf bound_ctrl:1
	v_add_f32_dpp v146, v146, v146 row_ror:8 row_mask:0xf bank_mask:0xf bound_ctrl:1
	v_add_f32_dpp v149, v149, v149 row_ror:8 row_mask:0xf bank_mask:0xf bound_ctrl:1
	v_add_f32_dpp v161, v161, v161 row_ror:8 row_mask:0xf bank_mask:0xf bound_ctrl:1
	v_add_f32_dpp v164, v164, v164 row_ror:8 row_mask:0xf bank_mask:0xf bound_ctrl:1
	v_add_f32_dpp v165, v165, v165 row_ror:8 row_mask:0xf bank_mask:0xf bound_ctrl:1
	v_add_f32_dpp v169, v166, v166 row_ror:8 row_mask:0xf bank_mask:0xf bound_ctrl:1
	v_add_f32_dpp v167, v167, v167 row_ror:8 row_mask:0xf bank_mask:0xf bound_ctrl:1
	v_add_f32_dpp v171, v168, v168 row_ror:8 row_mask:0xf bank_mask:0xf bound_ctrl:1
	ds_bpermute_b32 v166, v184, v146
	ds_bpermute_b32 v168, v184, v149
	ds_bpermute_b32 v170, v184, v161
	ds_bpermute_b32 v187, v184, v164
	ds_bpermute_b32 v188, v184, v165
	ds_bpermute_b32 v189, v184, v169
	ds_bpermute_b32 v190, v184, v167
	ds_bpermute_b32 v191, v184, v171
	s_waitcnt lgkmcnt(7)
	v_add_f32_e32 v146, v146, v166
	s_waitcnt lgkmcnt(6)
	v_add_f32_e32 v149, v149, v168
	s_waitcnt lgkmcnt(5)
	v_add_f32_e32 v161, v161, v170
	s_waitcnt lgkmcnt(4)
	v_add_f32_e32 v164, v164, v187
	s_waitcnt lgkmcnt(3)
	v_add_f32_e32 v166, v165, v188
	s_waitcnt lgkmcnt(2)
	v_add_f32_e32 v168, v169, v189
	s_waitcnt lgkmcnt(1)
	v_add_f32_e32 v170, v167, v190
	s_waitcnt lgkmcnt(0)
	v_add_f32_e32 v187, v171, v191
	ds_bpermute_b32 v165, v185, v146
	ds_bpermute_b32 v167, v185, v149
	ds_bpermute_b32 v169, v185, v161
	ds_bpermute_b32 v171, v185, v164
	ds_bpermute_b32 v188, v185, v166
	ds_bpermute_b32 v189, v185, v168
	ds_bpermute_b32 v190, v185, v170
	ds_bpermute_b32 v191, v185, v187
	v_cvt_pk_bf16_f32 v192, v192, v193
	v_cvt_pk_bf16_f32 v193, v194, v195
	global_store_dwordx2 v[162:163], v[192:193], off offset:1536
	s_and_saveexec_b64 s[24:25], vcc
	s_cbranch_execz .LBB0_60
	s_waitcnt lgkmcnt(7)
	v_add_f32_e32 v146, v146, v165
	s_waitcnt lgkmcnt(6)
	v_add_f32_e32 v149, v149, v167
	v_cndmask_b32_e64 v165, 0, v146, s[14:15]
	s_waitcnt lgkmcnt(5)
	v_add_f32_e32 v169, v161, v169
	v_cndmask_b32_e64 v149, v165, v149, s[12:13]
	s_waitcnt lgkmcnt(4)
	v_add_f32_e32 v164, v164, v171
	v_cndmask_b32_e64 v149, v149, v169, s[10:11]
	s_waitcnt lgkmcnt(3)
	v_add_f32_e32 v166, v166, v188
	v_cndmask_b32_e64 v149, v149, v164, s[8:9]
	s_waitcnt lgkmcnt(2)
	v_add_f32_e32 v168, v168, v189
	v_cndmask_b32_e64 v149, v149, v166, s[6:7]
	s_waitcnt lgkmcnt(1)
	v_add_f32_e32 v170, v170, v190
	v_cndmask_b32_e64 v149, v149, v168, s[4:5]
	s_waitcnt lgkmcnt(0)
	v_add_f32_e32 v163, v187, v191
	v_cndmask_b32_e64 v149, v149, v170, s[16:17]
	v_cndmask_b32_e64 v149, v149, v163, s[0:1]
	v_and_b32_e32 v161, 0x7ff, v160
	v_ashrrev_i32_e32 v160, 8, v160
	v_and_or_b32 v160, v160, -8, v183
	v_lshlrev_b32_e32 v146, 2, v161
	v_ashrrev_i32_e32 v161, 31, v160
	v_lshlrev_b64 v[160:161], 13, v[160:161]
	v_lshl_add_u64 v[160:161], s[22:23], 0, v[160:161]
	v_lshl_add_u64 v[160:161], v[160:161], 0, v[146:147]
	v_add_f32_e32 v149, v149, v246
	v_mul_f32_e64 v162, |v149|, s34
	v_exp_f32_e32 v187, v162
	v_min_f32_e32 v192, 0, v149
	v_add_f32_e32 v149, 1.0, v187
	v_add_f32_e32 v164, -1.0, v149
	v_frexp_mant_f32_e32 v165, v149
	v_cvt_f64_f32_e32 v[162:163], v149
	v_sub_f32_e32 v166, v164, v149
	v_frexp_exp_i32_f64_e32 v162, v[162:163]
	v_cmp_gt_f32_e64 s[18:19], s35, v165
	v_sub_f32_e32 v164, v187, v164
	v_add_f32_e32 v163, 1.0, v166
	v_subbrev_co_u32_e64 v162, s[18:19], 0, v162, s[18:19]
	v_add_f32_e32 v163, v164, v163
	v_sub_u32_e32 v164, 0, v162
	v_ldexp_f32 v149, v149, v164
	v_ldexp_f32 v163, v163, v164
	v_add_f32_e32 v164, -1.0, v149
	v_add_f32_e32 v166, 1.0, v149
	v_add_f32_e32 v165, 1.0, v164
	v_add_f32_e32 v167, -1.0, v166
	v_sub_f32_e32 v165, v149, v165
	v_sub_f32_e32 v149, v149, v167
	v_add_f32_e32 v149, v163, v149
	v_add_f32_e32 v167, v163, v165
	v_add_f32_e32 v163, v166, v149
	v_rcp_f32_e32 v170, v163
	v_add_f32_e32 v165, v164, v167
	v_sub_f32_e32 v166, v163, v166
	v_sub_f32_e32 v149, v149, v166
	v_mul_f32_e32 v188, v165, v170
	v_mul_f32_e32 v166, v163, v188
	v_fma_f32 v168, v188, v163, -v166
	v_sub_f32_e32 v164, v165, v164
	v_fmac_f32_e32 v168, v188, v149
	v_sub_f32_e32 v171, v167, v164
	v_add_f32_e32 v164, v166, v168
	v_sub_f32_e32 v167, v165, v164
	v_mov_b32_e32 v169, v164
	v_pk_add_f32 v[164:165], v[164:165], v[166:167] neg_lo:[0,1] neg_hi:[0,1]
	v_cvt_f32_i32_e32 v162, v162
	v_pk_add_f32 v[164:165], v[164:165], v[168:169] neg_lo:[0,1] neg_hi:[0,1]
	v_cmp_neq_f32_e64 s[18:19], s37, v187
	v_add_f32_e32 v165, v171, v165
	v_add_f32_e32 v164, v164, v165
	v_add_f32_e32 v165, v167, v164
	v_mul_f32_e32 v169, v170, v165
	v_mul_f32_e32 v166, v163, v169
	v_fma_f32 v168, v169, v163, -v166
	v_sub_f32_e32 v167, v167, v165
	v_fmac_f32_e32 v168, v169, v149
	v_add_f32_e32 v171, v164, v167
	v_add_f32_e32 v189, v188, v169
	v_add_f32_e32 v164, v166, v168
	v_sub_f32_e32 v163, v189, v188
	v_sub_f32_e32 v167, v165, v164
	v_sub_f32_e32 v149, v169, v163
	v_mov_b32_e32 v169, v164
	v_pk_add_f32 v[164:165], v[164:165], v[166:167] neg_lo:[0,1] neg_hi:[0,1]
	s_nop 0
	v_pk_add_f32 v[164:165], v[164:165], v[168:169] neg_lo:[0,1] neg_hi:[0,1]
	s_nop 0
	v_add_f32_e32 v163, v171, v165
	v_add_f32_e32 v163, v164, v163
	v_add_f32_e32 v163, v167, v163
	v_mul_f32_e32 v163, v170, v163
	v_add_f32_e32 v149, v149, v163
	v_add_f32_e32 v163, v189, v149
	v_mul_f32_e32 v164, v163, v163
	v_sub_f32_e32 v166, v163, v189
	v_fmamk_f32 v167, v164, 0x3e9b6dac, v173
	v_ldexp_f32 v165, v163, 1
	v_sub_f32_e32 v166, v149, v166
	v_mul_f32_e32 v163, v163, v164
	v_fmaak_f32 v149, v164, v167, 0x3f2aaada
	v_ldexp_f32 v169, v166, 1
	v_pk_mul_f32 v[166:167], v[162:163], v[148:149]
	s_nop 0
	v_fma_f32 v164, v162, s36, -v166
	v_fmac_f32_e32 v164, 0xb102e308, v162
	v_pk_add_f32 v[162:163], v[166:167], v[164:165]
	v_mov_b32_e32 v168, v166
	v_sub_f32_e32 v149, v163, v165
	v_sub_f32_e32 v149, v167, v149
	v_add_f32_e32 v169, v169, v149
	v_pk_add_f32 v[170:171], v[162:163], v[166:167] neg_lo:[0,1] neg_hi:[0,1]
	v_pk_add_f32 v[166:167], v[162:163], v[168:169]
	v_mov_b32_e32 v165, v162
	v_mov_b32_e32 v171, v167
	v_pk_add_f32 v[190:191], v[164:165], v[170:171] neg_lo:[0,1] neg_hi:[0,1]
	v_pk_add_f32 v[164:165], v[164:165], v[170:171]
	v_mov_b32_e32 v189, v162
	v_pk_add_f32 v[170:171], v[164:165], v[162:163] op_sel:[1,0] op_sel_hi:[0,1] neg_lo:[0,1] neg_hi:[0,1]
	v_mov_b32_e32 v188, v169
	v_mov_b32_e32 v168, v167
	v_mov_b32_e32 v169, v165
	v_pk_mov_b32 v[162:163], v[162:163], v[170:171] op_sel:[1,0]
	v_pk_add_f32 v[166:167], v[166:167], v[170:171] op_sel_hi:[1,0] neg_lo:[0,1] neg_hi:[0,1]
	v_pk_add_f32 v[162:163], v[168:169], v[162:163] neg_lo:[0,1] neg_hi:[0,1]
	v_mov_b32_e32 v166, v190
	v_pk_add_f32 v[162:163], v[188:189], v[162:163] neg_lo:[0,1] neg_hi:[0,1]
	v_mov_b32_e32 v191, v165
	v_pk_add_f32 v[166:167], v[166:167], v[162:163]
	s_nop 0
	v_pk_add_f32 v[168:169], v[166:167], v[166:167] op_sel:[0,1] op_sel_hi:[1,0]
	s_nop 0
	v_pk_add_f32 v[164:165], v[164:165], v[168:169] op_sel:[1,0] op_sel_hi:[0,1]
	v_mov_b32_e32 v167, v164
	v_mov_b32_e32 v163, v168
	v_pk_add_f32 v[168:169], v[166:167], v[190:191] neg_lo:[0,1] neg_hi:[0,1]
	s_nop 0
	v_sub_f32_e32 v149, v166, v168
	v_pk_add_f32 v[162:163], v[162:163], v[168:169] neg_lo:[0,1] neg_hi:[0,1]
	v_sub_f32_e32 v149, v190, v149
	v_add_f32_e32 v149, v162, v149
	v_add_f32_e32 v149, v149, v163
	v_add_f32_e32 v149, v164, v149
	v_cndmask_b32_e64 v149, v180, v149, s[18:19]
	v_cmp_ngt_f32_e64 s[18:19], -1.0, v187
	s_nop 1
	v_cndmask_b32_e64 v149, v181, v149, s[18:19]
	v_cmp_neq_f32_e64 s[18:19], -1.0, v187
	s_nop 1
	v_cndmask_b32_e64 v149, v182, v149, s[18:19]
	v_cmp_lt_f32_e64 s[18:19], |v187|, s38
	s_nop 1
	v_cndmask_b32_e64 v149, v149, v187, s[18:19]
	v_sub_f32_e32 v149, v192, v149
	global_store_dword v[160:161], v149, off
	s_branch .LBB0_60
